# attention loop: bias / rescale / post-rescale blocks out of line (flag subs kept inline)
# speedup vs baseline: 1.0132x; 1.0132x over previous
.LBB0_882:
	s_waitcnt lgkmcnt(0)
	s_barrier
	s_cbranch_scc1 .Lq1_body
	s_branch .Lq1_last
.Lq1_o_bias1:
	v_add_u32_e32 v0, s87, v217
	v_add_u32_e32 v154, 0x80, v0
	v_max_i32_e32 v3, -1, v154
	v_max_i32_e32 v148, -2, v154
	v_max_i32_e32 v149, -3, v154
	v_max_i32_e32 v150, -16, v154
	v_max_i32_e32 v151, 0xffffffef, v154
	v_max_i32_e32 v152, 0xffffffee, v154
	v_max_i32_e32 v153, 0xffffffed, v154
	v_add_u32_e32 v3, 1, v3
	v_add_u32_e32 v148, 2, v148
	v_add_u32_e32 v149, 3, v149
	v_add_u32_e32 v150, 16, v150
	v_add_u32_e32 v151, 17, v151
	v_add_u32_e32 v152, 18, v152
	v_add_u32_e32 v153, 19, v153
	v_med3_i32 v2, v154, 0, v209
	v_min_u32_e32 v3, 0xff, v3
	v_min_u32_e32 v148, 0xff, v148
	v_min_u32_e32 v149, 0xff, v149
	v_min_u32_e32 v150, 0xff, v150
	v_min_u32_e32 v151, 0xff, v151
	v_min_u32_e32 v152, 0xff, v152
	v_min_u32_e32 v153, 0xff, v153
	v_lshl_add_u32 v2, v2, 2, s71
	v_lshl_add_u32 v3, v3, 2, s71
	v_lshl_add_u32 v148, v148, 2, s71
	v_lshl_add_u32 v149, v149, 2, s71
	v_lshl_add_u32 v150, v150, 2, s71
	v_lshl_add_u32 v151, v151, 2, s71
	v_lshl_add_u32 v152, v152, 2, s71
	v_lshl_add_u32 v153, v153, 2, s71
	ds_read_b32 v2, v2
	ds_read_b32 v3, v3
	ds_read_b32 v148, v148
	ds_read_b32 v149, v149
	ds_read_b32 v150, v150
	ds_read_b32 v151, v151
	ds_read_b32 v152, v152
	ds_read_b32 v153, v153
	s_waitcnt lgkmcnt(4)
	v_pk_add_f32 v[146:147], v[146:147], v[148:149]
	v_pk_add_f32 v[144:145], v[144:145], v[2:3]
	v_max_i32_e32 v2, 0xffffffe0, v154
	v_max_i32_e32 v3, 0xffffffdf, v154
	v_max_i32_e32 v148, 0xffffffde, v154
	v_max_i32_e32 v149, 0xffffffdd, v154
	v_max_i32_e32 v155, 0xffffffd0, v154
	v_max_i32_e32 v156, 0xffffffcf, v154
	v_max_i32_e32 v157, 0xffffffce, v154
	v_add_u32_e32 v2, 32, v2
	v_add_u32_e32 v3, 33, v3
	v_add_u32_e32 v148, 34, v148
	v_add_u32_e32 v149, 35, v149
	v_add_u32_e32 v155, 48, v155
	v_add_u32_e32 v156, 49, v156
	v_add_u32_e32 v157, 50, v157
	v_max_i32_e32 v154, 0xffffffcd, v154
	v_min_u32_e32 v2, 0xff, v2
	v_min_u32_e32 v3, 0xff, v3
	v_min_u32_e32 v148, 0xff, v148
	v_min_u32_e32 v149, 0xff, v149
	v_min_u32_e32 v155, 0xff, v155
	v_min_u32_e32 v156, 0xff, v156
	v_min_u32_e32 v157, 0xff, v157
	v_add_u32_e32 v154, 51, v154
	v_lshl_add_u32 v2, v2, 2, s71
	v_lshl_add_u32 v3, v3, 2, s71
	v_lshl_add_u32 v148, v148, 2, s71
	v_lshl_add_u32 v149, v149, 2, s71
	v_lshl_add_u32 v155, v155, 2, s71
	v_lshl_add_u32 v156, v156, 2, s71
	v_lshl_add_u32 v157, v157, 2, s71
	v_min_u32_e32 v154, 0xff, v154
	v_lshl_add_u32 v158, v154, 2, s71
	ds_read_b32 v2, v2
	ds_read_b32 v3, v3
	ds_read_b32 v148, v148
	ds_read_b32 v149, v149
	ds_read_b32 v154, v155
	ds_read_b32 v155, v156
	ds_read_b32 v156, v157
	ds_read_b32 v157, v158
	v_add_u32_e32 v0, 0x70, v0
	s_waitcnt lgkmcnt(8)
	v_pk_add_f32 v[46:47], v[46:47], v[152:153]
	v_pk_add_f32 v[44:45], v[44:45], v[150:151]
	s_waitcnt lgkmcnt(4)
	v_pk_add_f32 v[142:143], v[142:143], v[148:149]
	v_pk_add_f32 v[140:141], v[140:141], v[2:3]
	v_max_i32_e32 v3, -1, v0
	v_max_i32_e32 v148, -2, v0
	v_max_i32_e32 v149, -3, v0
	v_max_i32_e32 v150, -16, v0
	v_max_i32_e32 v151, 0xffffffef, v0
	v_max_i32_e32 v152, 0xffffffee, v0
	v_max_i32_e32 v153, 0xffffffed, v0
	v_add_u32_e32 v3, 1, v3
	v_add_u32_e32 v148, 2, v148
	v_add_u32_e32 v149, 3, v149
	v_add_u32_e32 v150, 16, v150
	v_add_u32_e32 v151, 17, v151
	v_add_u32_e32 v152, 18, v152
	v_add_u32_e32 v153, 19, v153
	v_med3_i32 v2, v0, 0, v209
	v_min_u32_e32 v3, 0xff, v3
	v_min_u32_e32 v148, 0xff, v148
	v_min_u32_e32 v149, 0xff, v149
	v_min_u32_e32 v150, 0xff, v150
	v_min_u32_e32 v151, 0xff, v151
	v_min_u32_e32 v152, 0xff, v152
	v_min_u32_e32 v153, 0xff, v153
	v_lshl_add_u32 v2, v2, 2, s71
	v_lshl_add_u32 v3, v3, 2, s71
	v_lshl_add_u32 v148, v148, 2, s71
	v_lshl_add_u32 v149, v149, 2, s71
	v_lshl_add_u32 v150, v150, 2, s71
	v_lshl_add_u32 v151, v151, 2, s71
	v_lshl_add_u32 v152, v152, 2, s71
	v_lshl_add_u32 v153, v153, 2, s71
	ds_read_b32 v2, v2
	ds_read_b32 v3, v3
	ds_read_b32 v148, v148
	ds_read_b32 v149, v149
	ds_read_b32 v150, v150
	ds_read_b32 v151, v151
	ds_read_b32 v152, v152
	ds_read_b32 v153, v153
	s_waitcnt lgkmcnt(8)
	v_pk_add_f32 v[74:75], v[74:75], v[156:157]
	v_pk_add_f32 v[72:73], v[72:73], v[154:155]
	s_waitcnt lgkmcnt(4)
	v_pk_add_f32 v[138:139], v[138:139], v[148:149]
	v_pk_add_f32 v[136:137], v[136:137], v[2:3]
	v_max_i32_e32 v2, 0xffffffe0, v0
	v_max_i32_e32 v3, 0xffffffdf, v0
	v_max_i32_e32 v148, 0xffffffde, v0
	v_max_i32_e32 v149, 0xffffffdd, v0
	v_max_i32_e32 v154, 0xffffffd0, v0
	v_max_i32_e32 v155, 0xffffffcf, v0
	v_max_i32_e32 v156, 0xffffffce, v0
	v_add_u32_e32 v2, 32, v2
	v_add_u32_e32 v3, 33, v3
	v_add_u32_e32 v148, 34, v148
	v_add_u32_e32 v149, 35, v149
	v_add_u32_e32 v154, 48, v154
	v_add_u32_e32 v155, 49, v155
	v_add_u32_e32 v156, 50, v156
	v_max_i32_e32 v0, 0xffffffcd, v0
	v_min_u32_e32 v2, 0xff, v2
	v_min_u32_e32 v3, 0xff, v3
	v_min_u32_e32 v148, 0xff, v148
	v_min_u32_e32 v149, 0xff, v149
	v_min_u32_e32 v154, 0xff, v154
	v_min_u32_e32 v155, 0xff, v155
	v_min_u32_e32 v156, 0xff, v156
	v_add_u32_e32 v0, 51, v0
	v_lshl_add_u32 v2, v2, 2, s71
	v_lshl_add_u32 v3, v3, 2, s71
	v_lshl_add_u32 v148, v148, 2, s71
	v_lshl_add_u32 v149, v149, 2, s71
	v_lshl_add_u32 v154, v154, 2, s71
	v_lshl_add_u32 v155, v155, 2, s71
	v_lshl_add_u32 v156, v156, 2, s71
	v_min_u32_e32 v0, 0xff, v0
	v_lshl_add_u32 v0, v0, 2, s71
	ds_read_b32 v2, v2
	ds_read_b32 v3, v3
	ds_read_b32 v148, v148
	ds_read_b32 v149, v149
	ds_read_b32 v154, v154
	ds_read_b32 v155, v155
	ds_read_b32 v156, v156
	ds_read_b32 v157, v0
	s_waitcnt lgkmcnt(8)
	v_pk_add_f32 v[94:95], v[94:95], v[152:153]
	v_pk_add_f32 v[92:93], v[92:93], v[150:151]
	s_waitcnt lgkmcnt(4)
	v_pk_add_f32 v[134:135], v[134:135], v[148:149]
	v_pk_add_f32 v[132:133], v[132:133], v[2:3]
	s_waitcnt lgkmcnt(0)
	v_pk_add_f32 v[114:115], v[114:115], v[156:157]
	v_pk_add_f32 v[112:113], v[112:113], v[154:155]
	s_branch .LBB0_861

.Lq1_o_post1:
	v_mov_b32_e32 v0, v210
	s_nop 0
	v_lshlrev_b32_e32 v0, 2, v0
	v_and_b32_e32 v0, 60, v0
	v_and_or_b32 v0, v212, 64, v0
	v_lshlrev_b32_e32 v0, 2, v0
	ds_bpermute_b32 v48, v0, v200
	ds_bpermute_b32 v50, v0, v200 offset:8
	ds_bpermute_b32 v51, v0, v200 offset:12
	ds_bpermute_b32 v49, v0, v200 offset:4
	ds_bpermute_b32 v56, v0, v201
	ds_bpermute_b32 v58, v0, v201 offset:8
	ds_bpermute_b32 v59, v0, v201 offset:12
	ds_bpermute_b32 v57, v0, v201 offset:4
	s_waitcnt lgkmcnt(5)
	v_pk_mul_f32 v[146:147], v[146:147], v[50:51]
	s_waitcnt lgkmcnt(4)
	v_pk_mul_f32 v[144:145], v[144:145], v[48:49]
	v_pk_mul_f32 v[150:151], v[150:151], v[50:51]
	v_pk_mul_f32 v[148:149], v[148:149], v[48:49]
	v_pk_mul_f32 v[158:159], v[158:159], v[50:51]
	v_pk_mul_f32 v[156:157], v[156:157], v[48:49]
	v_pk_mul_f32 v[166:167], v[166:167], v[50:51]
	v_pk_mul_f32 v[164:165], v[164:165], v[48:49]
	v_pk_mul_f32 v[174:175], v[174:175], v[50:51]
	v_pk_mul_f32 v[172:173], v[172:173], v[48:49]
	v_pk_mul_f32 v[178:179], v[178:179], v[50:51]
	v_pk_mul_f32 v[176:177], v[176:177], v[48:49]
	v_pk_mul_f32 v[186:187], v[186:187], v[50:51]
	v_pk_mul_f32 v[184:185], v[184:185], v[48:49]
	v_pk_mul_f32 v[194:195], v[194:195], v[50:51]
	v_pk_mul_f32 v[192:193], v[192:193], v[48:49]
	s_waitcnt lgkmcnt(1)
	v_pk_mul_f32 v[142:143], v[142:143], v[58:59]
	s_waitcnt lgkmcnt(0)
	v_pk_mul_f32 v[140:141], v[140:141], v[56:57]
	v_pk_mul_f32 v[138:139], v[138:139], v[58:59]
	v_pk_mul_f32 v[136:137], v[136:137], v[56:57]
	v_pk_mul_f32 v[154:155], v[154:155], v[58:59]
	v_pk_mul_f32 v[152:153], v[152:153], v[56:57]
	v_pk_mul_f32 v[162:163], v[162:163], v[58:59]
	v_pk_mul_f32 v[160:161], v[160:161], v[56:57]
	v_pk_mul_f32 v[170:171], v[170:171], v[58:59]
	v_pk_mul_f32 v[168:169], v[168:169], v[56:57]
	v_pk_mul_f32 v[134:135], v[134:135], v[58:59]
	v_pk_mul_f32 v[132:133], v[132:133], v[56:57]
	v_pk_mul_f32 v[182:183], v[182:183], v[58:59]
	v_pk_mul_f32 v[180:181], v[180:181], v[56:57]
	v_pk_mul_f32 v[190:191], v[190:191], v[58:59]
	v_pk_mul_f32 v[188:189], v[188:189], v[56:57]
	s_branch .LBB0_865
.Lq1_o_bias2:
	v_add_u32_e32 v0, s87, v217
	v_add_u32_e32 v102, 0xc0, v0
	v_max_i32_e32 v3, -1, v102
	v_max_i32_e32 v124, -2, v102
	v_max_i32_e32 v125, -3, v102
	v_max_i32_e32 v126, -16, v102
	v_max_i32_e32 v127, 0xffffffef, v102
	v_max_i32_e32 v100, 0xffffffee, v102
	v_max_i32_e32 v101, 0xffffffed, v102
	v_add_u32_e32 v3, 1, v3
	v_add_u32_e32 v124, 2, v124
	v_add_u32_e32 v125, 3, v125
	v_add_u32_e32 v126, 16, v126
	v_add_u32_e32 v127, 17, v127
	v_add_u32_e32 v100, 18, v100
	v_add_u32_e32 v101, 19, v101
	v_med3_i32 v2, v102, 0, v209
	v_min_u32_e32 v3, 0xff, v3
	v_min_u32_e32 v124, 0xff, v124
	v_min_u32_e32 v125, 0xff, v125
	v_min_u32_e32 v126, 0xff, v126
	v_min_u32_e32 v127, 0xff, v127
	v_min_u32_e32 v100, 0xff, v100
	v_min_u32_e32 v101, 0xff, v101
	v_lshl_add_u32 v2, v2, 2, s71
	v_lshl_add_u32 v3, v3, 2, s71
	v_lshl_add_u32 v124, v124, 2, s71
	v_lshl_add_u32 v125, v125, 2, s71
	v_lshl_add_u32 v126, v126, 2, s71
	v_lshl_add_u32 v127, v127, 2, s71
	v_lshl_add_u32 v100, v100, 2, s71
	v_lshl_add_u32 v101, v101, 2, s71
	ds_read_b32 v2, v2
	ds_read_b32 v3, v3
	ds_read_b32 v124, v124
	ds_read_b32 v125, v125
	ds_read_b32 v126, v126
	ds_read_b32 v127, v127
	ds_read_b32 v100, v100
	ds_read_b32 v101, v101
	s_waitcnt lgkmcnt(4)
	v_pk_add_f32 v[130:131], v[130:131], v[124:125]
	v_pk_add_f32 v[128:129], v[128:129], v[2:3]
	v_max_i32_e32 v2, 0xffffffe0, v102
	v_max_i32_e32 v3, 0xffffffdf, v102
	v_max_i32_e32 v124, 0xffffffde, v102
	v_max_i32_e32 v125, 0xffffffdd, v102
	v_max_i32_e32 v103, 0xffffffd0, v102
	v_max_i32_e32 v116, 0xffffffcf, v102
	v_max_i32_e32 v117, 0xffffffce, v102
	v_add_u32_e32 v2, 32, v2
	v_add_u32_e32 v3, 33, v3
	v_add_u32_e32 v124, 34, v124
	v_add_u32_e32 v125, 35, v125
	v_add_u32_e32 v103, 48, v103
	v_add_u32_e32 v116, 49, v116
	v_add_u32_e32 v117, 50, v117
	v_max_i32_e32 v102, 0xffffffcd, v102
	v_min_u32_e32 v2, 0xff, v2
	v_min_u32_e32 v3, 0xff, v3
	v_min_u32_e32 v124, 0xff, v124
	v_min_u32_e32 v125, 0xff, v125
	v_min_u32_e32 v103, 0xff, v103
	v_min_u32_e32 v116, 0xff, v116
	v_min_u32_e32 v117, 0xff, v117
	v_add_u32_e32 v102, 51, v102
	v_lshl_add_u32 v2, v2, 2, s71
	v_lshl_add_u32 v3, v3, 2, s71
	v_lshl_add_u32 v124, v124, 2, s71
	v_lshl_add_u32 v125, v125, 2, s71
	v_lshl_add_u32 v103, v103, 2, s71
	v_lshl_add_u32 v116, v116, 2, s71
	v_lshl_add_u32 v117, v117, 2, s71
	v_min_u32_e32 v102, 0xff, v102
	v_lshl_add_u32 v118, v102, 2, s71
	ds_read_b32 v2, v2
	ds_read_b32 v3, v3
	ds_read_b32 v124, v124
	ds_read_b32 v125, v125
	ds_read_b32 v102, v103
	ds_read_b32 v103, v116
	ds_read_b32 v116, v117
	ds_read_b32 v117, v118
	v_add_u32_e32 v0, 0xb0, v0
	s_waitcnt lgkmcnt(8)
	v_pk_add_f32 v[38:39], v[38:39], v[100:101]
	v_pk_add_f32 v[36:37], v[36:37], v[126:127]
	s_waitcnt lgkmcnt(4)
	v_pk_add_f32 v[122:123], v[122:123], v[124:125]
	v_pk_add_f32 v[120:121], v[120:121], v[2:3]
	v_max_i32_e32 v3, -1, v0
	v_max_i32_e32 v124, -2, v0
	v_max_i32_e32 v125, -3, v0
	v_max_i32_e32 v126, -16, v0
	v_max_i32_e32 v127, 0xffffffef, v0
	v_max_i32_e32 v100, 0xffffffee, v0
	v_max_i32_e32 v101, 0xffffffed, v0
	v_add_u32_e32 v3, 1, v3
	v_add_u32_e32 v124, 2, v124
	v_add_u32_e32 v125, 3, v125
	v_add_u32_e32 v126, 16, v126
	v_add_u32_e32 v127, 17, v127
	v_add_u32_e32 v100, 18, v100
	v_add_u32_e32 v101, 19, v101
	v_med3_i32 v2, v0, 0, v209
	v_min_u32_e32 v3, 0xff, v3
	v_min_u32_e32 v124, 0xff, v124
	v_min_u32_e32 v125, 0xff, v125
	v_min_u32_e32 v126, 0xff, v126
	v_min_u32_e32 v127, 0xff, v127
	v_min_u32_e32 v100, 0xff, v100
	v_min_u32_e32 v101, 0xff, v101
	v_lshl_add_u32 v2, v2, 2, s71
	v_lshl_add_u32 v3, v3, 2, s71
	v_lshl_add_u32 v124, v124, 2, s71
	v_lshl_add_u32 v125, v125, 2, s71
	v_lshl_add_u32 v126, v126, 2, s71
	v_lshl_add_u32 v127, v127, 2, s71
	v_lshl_add_u32 v100, v100, 2, s71
	v_lshl_add_u32 v101, v101, 2, s71
	ds_read_b32 v2, v2
	ds_read_b32 v3, v3
	ds_read_b32 v124, v124
	ds_read_b32 v125, v125
	ds_read_b32 v126, v126
	ds_read_b32 v127, v127
	ds_read_b32 v100, v100
	ds_read_b32 v101, v101
	s_waitcnt lgkmcnt(8)
	v_pk_add_f32 v[42:43], v[42:43], v[116:117]
	v_pk_add_f32 v[40:41], v[40:41], v[102:103]
	s_waitcnt lgkmcnt(4)
	v_pk_add_f32 v[110:111], v[110:111], v[124:125]
	v_pk_add_f32 v[108:109], v[108:109], v[2:3]
	v_max_i32_e32 v2, 0xffffffe0, v0
	v_max_i32_e32 v3, 0xffffffdf, v0
	v_max_i32_e32 v124, 0xffffffde, v0
	v_max_i32_e32 v125, 0xffffffdd, v0
	v_max_i32_e32 v102, 0xffffffd0, v0
	v_max_i32_e32 v103, 0xffffffcf, v0
	v_max_i32_e32 v116, 0xffffffce, v0
	v_add_u32_e32 v2, 32, v2
	v_add_u32_e32 v3, 33, v3
	v_add_u32_e32 v124, 34, v124
	v_add_u32_e32 v125, 35, v125
	v_add_u32_e32 v102, 48, v102
	v_add_u32_e32 v103, 49, v103
	v_add_u32_e32 v116, 50, v116
	v_max_i32_e32 v0, 0xffffffcd, v0
	v_min_u32_e32 v2, 0xff, v2
	v_min_u32_e32 v3, 0xff, v3
	v_min_u32_e32 v124, 0xff, v124
	v_min_u32_e32 v125, 0xff, v125
	v_min_u32_e32 v102, 0xff, v102
	v_min_u32_e32 v103, 0xff, v103
	v_min_u32_e32 v116, 0xff, v116
	v_add_u32_e32 v0, 51, v0
	v_lshl_add_u32 v2, v2, 2, s71
	v_lshl_add_u32 v3, v3, 2, s71
	v_lshl_add_u32 v124, v124, 2, s71
	v_lshl_add_u32 v125, v125, 2, s71
	v_lshl_add_u32 v102, v102, 2, s71
	v_lshl_add_u32 v103, v103, 2, s71
	v_lshl_add_u32 v116, v116, 2, s71
	v_min_u32_e32 v0, 0xff, v0
	v_lshl_add_u32 v0, v0, 2, s71
	ds_read_b32 v2, v2
	ds_read_b32 v3, v3
	ds_read_b32 v124, v124
	ds_read_b32 v125, v125
	ds_read_b32 v102, v102
	ds_read_b32 v103, v103
	ds_read_b32 v116, v116
	ds_read_b32 v117, v0
	s_waitcnt lgkmcnt(8)
	v_pk_add_f32 v[62:63], v[62:63], v[100:101]
	v_pk_add_f32 v[60:61], v[60:61], v[126:127]
	s_waitcnt lgkmcnt(4)
	v_pk_add_f32 v[66:67], v[66:67], v[124:125]
	v_pk_add_f32 v[64:65], v[64:65], v[2:3]
	s_waitcnt lgkmcnt(0)
	v_pk_add_f32 v[86:87], v[86:87], v[116:117]
	v_pk_add_f32 v[84:85], v[84:85], v[102:103]
	s_branch .LBB0_877
